# P8 norm loop: next iteration's rows touched (loads to a dummy register) during the current iteration's compute
# speedup vs baseline: 1.0024x; 1.0014x over previous
.LBB0_1142:
	v_mul_hi_i32 v2, v50, s71
	v_lshrrev_b32_e32 v3, 31, v2
	v_ashrrev_i32_e32 v2, 9, v2
	v_add_u32_e32 v2, v2, v3
	v_mad_i32_i24 v3, v2, s73, v50
	s_movk_i32 s10, 0xff
	v_cmp_lt_i32_e32 vcc, s10, v3
	v_readlane_b32 s10, v255, 14
	v_readlane_b32 s11, v255, 15
	s_or_b64 s[12:13], s[10:11], vcc
	s_and_saveexec_b64 s[10:11], s[12:13]
	s_cbranch_execz .LBB0_1141
	v_ashrrev_i32_e32 v51, 31, v50
	v_lshlrev_b64 v[82:83], 11, v[50:51]
	v_lshl_add_u64 v[4:5], v[52:53], 0, v[82:83]
	global_load_dwordx4 v[46:49], v[4:5], off
	global_load_dwordx4 v[42:45], v[4:5], off offset:1024
	v_add_u32_e32 v4, 1, v50
	v_ashrrev_i32_e32 v5, 31, v4
	v_cndmask_b32_e32 v2, 32, v2, vcc
	v_readlane_b32 s12, v255, 9
	v_lshlrev_b64 v[80:81], 11, v[4:5]
	v_lshl_add_u64 v[4:5], v[52:53], 0, v[80:81]
	v_add_u32_e32 v2, s12, v2
	v_mul_i32_i24_e32 v2, 6, v2
	global_load_dwordx4 v[38:41], v[4:5], off
	global_load_dwordx4 v[34:37], v[4:5], off offset:1024
	v_add_u32_e32 v4, 2, v50
	v_ashrrev_i32_e32 v3, 31, v2
	v_ashrrev_i32_e32 v5, 31, v4
	v_lshlrev_b64 v[2:3], 12, v[2:3]
	v_lshlrev_b64 v[78:79], 11, v[4:5]
	v_lshl_add_u64 v[2:3], s[66:67], 0, v[2:3]
	v_lshl_add_u64 v[4:5], v[52:53], 0, v[78:79]
	s_mov_b64 s[12:13], 0x4000
	global_load_dwordx4 v[30:33], v[4:5], off
	global_load_dwordx4 v[26:29], v[4:5], off offset:1024
	v_add_u32_e32 v4, 3, v50
	v_lshl_add_u64 v[74:75], v[2:3], 0, s[12:13]
	v_lshl_add_u64 v[2:3], v[2:3], 0, v[0:1]
	s_mov_b64 s[12:13], 0x3000
	v_ashrrev_i32_e32 v5, 31, v4
	v_lshl_add_u64 v[76:77], v[2:3], 0, s[12:13]
	s_movk_i32 s12, 0x3000
	v_lshlrev_b64 v[60:61], 11, v[4:5]
	v_add_co_u32_e32 v2, vcc, s12, v2
	v_lshl_add_u64 v[4:5], v[52:53], 0, v[60:61]
	s_nop 0
	v_addc_co_u32_e32 v3, vcc, 0, v3, vcc
	v_lshl_add_u64 v[66:67], v[74:75], 0, v[0:1]
	global_load_dwordx4 v[22:25], v[4:5], off
	global_load_dwordx4 v[18:21], v[4:5], off offset:1024
	global_load_dwordx4 v[10:13], v[56:57], off offset:16
	global_load_dwordx4 v[14:17], v[56:57], off
	global_load_dwordx4 v[6:9], v[2:3], off
	s_nop 0
	global_load_dwordx4 v[2:5], v[76:77], off offset:16
	global_load_dwordx4 v[62:65], v[66:67], off offset:16
	s_nop 0
	global_load_dwordx4 v[66:69], v[66:67], off
	v_mov_b32_e32 v59, v1
	v_lshl_add_u64 v[74:75], v[74:75], 0, v[58:59]
	v_cmp_lt_i32_e32 vcc, v228, v225
	v_lshl_add_u64 v[82:83], v[54:55], 0, v[82:83]
	v_lshl_add_u64 v[80:81], v[54:55], 0, v[80:81]
	v_cndmask_b32_e32 v51, v224, v228, vcc
	v_lshlrev_b32_e32 v97, 2, v51
	v_cmp_lt_i32_e32 vcc, v227, v225
	s_waitcnt vmcnt(0)
	v_pk_add_f32 v[68:69], v[68:69], 1.0 op_sel_hi:[1,0]
	v_pk_add_f32 v[70:71], v[66:67], 1.0 op_sel_hi:[1,0]
	v_pk_mul_f32 v[66:67], v[16:17], v[68:69]
	v_pk_mul_f32 v[68:69], v[14:15], v[70:71]
	v_pk_add_f32 v[14:15], v[64:65], 1.0 op_sel_hi:[1,0]
	v_pk_add_f32 v[16:17], v[62:63], 1.0 op_sel_hi:[1,0]
	v_pk_mul_f32 v[62:63], v[12:13], v[14:15]
	v_pk_mul_f32 v[64:65], v[10:11], v[16:17]
	global_load_dwordx4 v[84:87], v[56:57], off offset:2064
	global_load_dwordx4 v[70:73], v[56:57], off offset:2048
	global_load_dwordx4 v[10:13], v[76:77], off offset:2064
	global_load_dwordx4 v[14:17], v[76:77], off offset:2048
	global_load_dwordx4 v[88:91], v[74:75], off offset:16
	s_nop 0
	global_load_dwordx4 v[74:77], v[74:75], off
	v_cndmask_b32_e32 v51, v224, v227, vcc
	v_lshlrev_b32_e32 v96, 2, v51
	v_cmp_lt_i32_e32 vcc, v226, v225
	s_waitcnt vmcnt(0)
	v_readlane_b32 s12, v255, 4
	s_nop 1
	v_add_u32_e32 v236, s12, v50
	v_ashrrev_i32_e32 v237, 31, v236
	v_lshlrev_b64 v[236:237], 11, v[236:237]
	v_lshl_add_u64 v[236:237], v[52:53], 0, v[236:237]
	global_load_dwordx4 v[240:243], v[236:237], off
	global_load_dwordx4 v[240:243], v[236:237], off offset:1024
	global_load_dwordx4 v[240:243], v[236:237], off offset:2048
	global_load_dwordx4 v[240:243], v[236:237], off offset:3072
	s_mov_b64 s[12:13], 0x1000
	v_lshl_add_u64 v[236:237], v[236:237], 0, s[12:13]
	global_load_dwordx4 v[240:243], v[236:237], off
	global_load_dwordx4 v[240:243], v[236:237], off offset:1024
	global_load_dwordx4 v[240:243], v[236:237], off offset:2048
	global_load_dwordx4 v[240:243], v[236:237], off offset:3072
	v_pk_add_f32 v[76:77], v[76:77], 1.0 op_sel_hi:[1,0]
	v_pk_add_f32 v[92:93], v[74:75], 1.0 op_sel_hi:[1,0]
	v_pk_mul_f32 v[74:75], v[72:73], v[76:77]
	v_pk_mul_f32 v[76:77], v[70:71], v[92:93]
	v_pk_add_f32 v[70:71], v[90:91], 1.0 op_sel_hi:[1,0]
	v_pk_add_f32 v[72:73], v[88:89], 1.0 op_sel_hi:[1,0]
	v_pk_mul_f32 v[70:71], v[86:87], v[70:71]
	v_and_b32_e32 v87, 0xffff0000, v48
	v_and_b32_e32 v86, 0xffff0000, v46
	v_lshlrev_b32_e32 v89, 16, v48
	v_lshlrev_b32_e32 v88, 16, v46
	v_lshlrev_b32_e32 v90, 16, v47
	v_and_b32_e32 v92, 0xffff0000, v47
	v_pk_mul_f32 v[46:47], v[86:87], v[86:87]
	v_lshlrev_b32_e32 v91, 16, v49
	v_pk_fma_f32 v[46:47], v[88:89], v[88:89], v[46:47]
	v_pk_mul_f32 v[72:73], v[84:85], v[72:73]
	v_and_b32_e32 v93, 0xffff0000, v49
	v_pk_fma_f32 v[46:47], v[90:91], v[90:91], v[46:47]
	v_and_b32_e32 v85, 0xffff0000, v42
	v_and_b32_e32 v84, 0xffff0000, v44
	v_pk_fma_f32 v[98:99], v[92:93], v[92:93], v[46:47]
	v_lshlrev_b32_e32 v47, 16, v42
	v_lshlrev_b32_e32 v46, 16, v44
	v_lshlrev_b32_e32 v48, 16, v45
	v_and_b32_e32 v42, 0xffff0000, v45
	v_pk_mul_f32 v[44:45], v[84:85], v[84:85]
	v_lshlrev_b32_e32 v49, 16, v43
	v_pk_fma_f32 v[44:45], v[46:47], v[46:47], v[44:45]
	v_and_b32_e32 v43, 0xffff0000, v43
	v_pk_fma_f32 v[44:45], v[48:49], v[48:49], v[44:45]
	v_add_f32_e32 v98, v98, v99
	v_pk_fma_f32 v[44:45], v[42:43], v[42:43], v[44:45]
	v_cndmask_b32_e32 v51, v224, v226, vcc
	v_add_f32_e32 v45, v98, v45
	v_add_f32_e32 v44, v44, v45
	ds_bpermute_b32 v45, v97, v44
	v_lshlrev_b32_e32 v95, 2, v51
	v_xor_b32_e32 v51, 4, v224
	v_cmp_lt_i32_e32 vcc, v51, v225
	v_mov_b32_e32 v98, v88
	s_waitcnt lgkmcnt(0)
	v_add_f32_e32 v44, v44, v45
	ds_bpermute_b32 v45, v96, v44
	v_cndmask_b32_e32 v51, v224, v51, vcc
	v_lshlrev_b32_e32 v94, 2, v51
	v_xor_b32_e32 v51, 2, v224
	v_cmp_lt_i32_e32 vcc, v51, v225
	s_waitcnt lgkmcnt(0)
	v_add_f32_e32 v44, v44, v45
	ds_bpermute_b32 v45, v95, v44
	v_cndmask_b32_e32 v51, v224, v51, vcc
	v_lshlrev_b32_e32 v59, 2, v51
	v_xor_b32_e32 v51, 1, v224
	v_cmp_lt_i32_e32 vcc, v51, v225
	s_waitcnt lgkmcnt(0)
	v_add_f32_e32 v44, v44, v45
	ds_bpermute_b32 v45, v94, v44
	v_cndmask_b32_e32 v51, v224, v51, vcc
	v_lshlrev_b32_e32 v51, 2, v51
	v_mov_b32_e32 v99, v86
	v_mov_b32_e32 v101, v92
	s_waitcnt lgkmcnt(0)
	v_add_f32_e32 v44, v44, v45
	ds_bpermute_b32 v45, v59, v44
	v_mov_b32_e32 v86, v89
	v_mov_b32_e32 v92, v91
	v_mov_b32_e32 v100, v90
	s_waitcnt lgkmcnt(0)
	v_add_f32_e32 v44, v44, v45
	ds_bpermute_b32 v45, v51, v44
	s_waitcnt lgkmcnt(0)
	v_add_f32_e32 v44, v44, v45
	v_fmamk_f32 v44, v44, 0x3a800000, v220
	v_cmp_gt_f32_e32 vcc, s93, v44
	v_mul_f32_e32 v45, 0x4b800000, v44
	s_nop 0
	v_cndmask_b32_e32 v44, v44, v45, vcc
	v_rsq_f32_e32 v44, v44
	s_nop 0
	v_mul_f32_e32 v45, 0x45800000, v44
	v_cndmask_b32_e32 v44, v44, v45, vcc
	v_pk_mul_f32 v[98:99], v[44:45], v[98:99] op_sel_hi:[0,1]
	v_pk_mul_f32 v[86:87], v[44:45], v[86:87] op_sel_hi:[0,1]
	v_pk_mul_f32 v[88:89], v[44:45], v[92:93] op_sel_hi:[0,1]
	v_pk_mul_f32 v[100:101], v[44:45], v[100:101] op_sel_hi:[0,1]
	v_pk_fma_f32 v[98:99], v[68:69], v[98:99], v[6:7]
	v_pk_fma_f32 v[90:91], v[62:63], v[88:89], v[4:5]
	v_pk_fma_f32 v[88:89], v[64:65], v[86:87], v[2:3]
	v_cvt_pk_bf16_f32 v86, v98, v99
	v_pk_fma_f32 v[100:101], v[66:67], v[100:101], v[8:9]
	s_nop 0
	v_cvt_pk_bf16_f32 v87, v100, v101
	v_cvt_pk_bf16_f32 v88, v88, v89
	v_cvt_pk_bf16_f32 v89, v90, v91
	global_store_dwordx4 v[82:83], v[86:89], off
	s_nop 1
	v_mov_b32_e32 v86, v47
	v_mov_b32_e32 v47, v84
	v_mov_b32_e32 v87, v85
	v_mov_b32_e32 v88, v49
	v_mov_b32_e32 v89, v43
	v_pk_mul_f32 v[46:47], v[44:45], v[46:47] op_sel_hi:[0,1]
	v_mov_b32_e32 v49, v42
	v_pk_mul_f32 v[86:87], v[44:45], v[86:87] op_sel_hi:[0,1]
	v_pk_mul_f32 v[88:89], v[44:45], v[88:89] op_sel_hi:[0,1]
	v_pk_mul_f32 v[42:43], v[44:45], v[48:49] op_sel_hi:[0,1]
	v_pk_fma_f32 v[44:45], v[72:73], v[46:47], v[10:11]
	v_pk_fma_f32 v[88:89], v[74:75], v[88:89], v[16:17]
	v_pk_fma_f32 v[86:87], v[76:77], v[86:87], v[14:15]
	v_pk_fma_f32 v[48:49], v[70:71], v[42:43], v[12:13]
	v_cvt_pk_bf16_f32 v42, v86, v87
	v_cvt_pk_bf16_f32 v43, v88, v89
	v_cvt_pk_bf16_f32 v44, v44, v45
	v_lshlrev_b32_e32 v46, 16, v39
	v_cvt_pk_bf16_f32 v45, v48, v49
	global_store_dwordx4 v[82:83], v[42:45], off offset:1024
	v_and_b32_e32 v83, 0xffff0000, v34
	v_and_b32_e32 v82, 0xffff0000, v36
	v_and_b32_e32 v45, 0xffff0000, v40
	v_and_b32_e32 v44, 0xffff0000, v38
	v_lshlrev_b32_e32 v43, 16, v40
	v_lshlrev_b32_e32 v42, 16, v38
	v_and_b32_e32 v40, 0xffff0000, v39
	v_pk_mul_f32 v[38:39], v[44:45], v[44:45]
	v_lshlrev_b32_e32 v47, 16, v41
	v_pk_fma_f32 v[38:39], v[42:43], v[42:43], v[38:39]
	v_lshlrev_b32_e32 v49, 16, v34
	v_lshlrev_b32_e32 v48, 16, v36
	v_lshlrev_b32_e32 v85, 16, v35
	v_and_b32_e32 v87, 0xffff0000, v35
	v_pk_mul_f32 v[34:35], v[82:83], v[82:83]
	v_and_b32_e32 v41, 0xffff0000, v41
	v_pk_fma_f32 v[38:39], v[46:47], v[46:47], v[38:39]
	v_lshlrev_b32_e32 v84, 16, v37
	v_pk_fma_f32 v[34:35], v[48:49], v[48:49], v[34:35]
	v_pk_fma_f32 v[38:39], v[40:41], v[40:41], v[38:39]
	v_and_b32_e32 v86, 0xffff0000, v37
	v_pk_fma_f32 v[34:35], v[84:85], v[84:85], v[34:35]
	v_add_f32_e32 v36, v38, v39
	v_pk_fma_f32 v[34:35], v[86:87], v[86:87], v[34:35]
	v_mov_b32_e32 v37, v40
	v_add_f32_e32 v35, v36, v35
	v_add_f32_e32 v34, v34, v35
	ds_bpermute_b32 v35, v97, v34
	v_mov_b32_e32 v36, v46
	v_mov_b32_e32 v40, v47
	v_and_b32_e32 v47, 0xffff0000, v27
	v_and_b32_e32 v46, 0xffff0000, v29
	s_waitcnt lgkmcnt(0)
	v_add_f32_e32 v34, v34, v35
	ds_bpermute_b32 v35, v96, v34
	s_waitcnt lgkmcnt(0)
	v_add_f32_e32 v34, v34, v35
	ds_bpermute_b32 v35, v95, v34
	s_waitcnt lgkmcnt(0)
	v_add_f32_e32 v34, v34, v35
	ds_bpermute_b32 v35, v94, v34
	s_waitcnt lgkmcnt(0)
	v_add_f32_e32 v34, v34, v35
	ds_bpermute_b32 v35, v59, v34
	s_waitcnt lgkmcnt(0)
	v_add_f32_e32 v34, v34, v35
	ds_bpermute_b32 v35, v51, v34
	s_waitcnt lgkmcnt(0)
	v_add_f32_e32 v34, v34, v35
	v_fmamk_f32 v34, v34, 0x3a800000, v220
	v_cmp_gt_f32_e32 vcc, s93, v34
	v_mul_f32_e32 v35, 0x4b800000, v34
	s_nop 0
	v_cndmask_b32_e32 v34, v34, v35, vcc
	v_rsq_f32_e32 v34, v34
	s_nop 0
	v_mul_f32_e32 v35, 0x45800000, v34
	v_cndmask_b32_e32 v38, v34, v35, vcc
	v_mov_b32_e32 v34, v42
	v_mov_b32_e32 v35, v44
	v_pk_mul_f32 v[34:35], v[38:39], v[34:35] op_sel_hi:[0,1]
	v_pk_mul_f32 v[36:37], v[38:39], v[36:37] op_sel_hi:[0,1]
	v_mov_b32_e32 v44, v43
	v_pk_fma_f32 v[36:37], v[66:67], v[36:37], v[8:9]
	v_pk_fma_f32 v[34:35], v[68:69], v[34:35], v[6:7]
	v_pk_mul_f32 v[42:43], v[38:39], v[44:45] op_sel_hi:[0,1]
	v_pk_mul_f32 v[40:41], v[38:39], v[40:41] op_sel_hi:[0,1]
	v_pk_fma_f32 v[40:41], v[62:63], v[40:41], v[4:5]
	v_pk_fma_f32 v[42:43], v[64:65], v[42:43], v[2:3]
	v_cvt_pk_bf16_f32 v34, v34, v35
	v_cvt_pk_bf16_f32 v35, v36, v37
	v_lshlrev_b32_e32 v45, 16, v27
	v_cvt_pk_bf16_f32 v36, v42, v43
	v_cvt_pk_bf16_f32 v37, v40, v41
	global_store_dwordx4 v[80:81], v[34:37], off
	v_and_b32_e32 v43, 0xffff0000, v26
	v_and_b32_e32 v42, 0xffff0000, v28
	v_mov_b32_e32 v34, v49
	v_mov_b32_e32 v35, v83
	v_mov_b32_e32 v36, v85
	v_mov_b32_e32 v37, v87
	v_pk_mul_f32 v[34:35], v[38:39], v[34:35] op_sel_hi:[0,1]
	v_pk_mul_f32 v[36:37], v[38:39], v[36:37] op_sel_hi:[0,1]
	v_mov_b32_e32 v49, v82
	v_mov_b32_e32 v85, v86
	v_pk_fma_f32 v[36:37], v[74:75], v[36:37], v[16:17]
	v_pk_fma_f32 v[34:35], v[76:77], v[34:35], v[14:15]
	v_pk_mul_f32 v[40:41], v[38:39], v[48:49] op_sel_hi:[0,1]
	v_pk_mul_f32 v[38:39], v[38:39], v[84:85] op_sel_hi:[0,1]
	v_pk_fma_f32 v[38:39], v[70:71], v[38:39], v[12:13]
	v_pk_fma_f32 v[40:41], v[72:73], v[40:41], v[10:11]
	v_cvt_pk_bf16_f32 v34, v34, v35
	v_cvt_pk_bf16_f32 v35, v36, v37
	v_lshlrev_b32_e32 v44, 16, v29
	v_cvt_pk_bf16_f32 v36, v40, v41
	v_cvt_pk_bf16_f32 v37, v38, v39
	global_store_dwordx4 v[80:81], v[34:37], off offset:1024
	v_lshlrev_b32_e32 v38, 16, v31
	v_lshlrev_b32_e32 v39, 16, v33
	v_and_b32_e32 v37, 0xffff0000, v32
	v_and_b32_e32 v36, 0xffff0000, v30
	v_lshlrev_b32_e32 v35, 16, v32
	v_lshlrev_b32_e32 v34, 16, v30
	v_and_b32_e32 v32, 0xffff0000, v31
	v_pk_mul_f32 v[30:31], v[36:37], v[36:37]
	v_lshlrev_b32_e32 v41, 16, v26
	v_pk_fma_f32 v[30:31], v[34:35], v[34:35], v[30:31]
	v_lshlrev_b32_e32 v40, 16, v28
	v_pk_mul_f32 v[26:27], v[42:43], v[42:43]
	v_and_b32_e32 v33, 0xffff0000, v33
	v_pk_fma_f32 v[30:31], v[38:39], v[38:39], v[30:31]
	v_pk_fma_f32 v[26:27], v[40:41], v[40:41], v[26:27]
	v_pk_fma_f32 v[30:31], v[32:33], v[32:33], v[30:31]
	v_pk_fma_f32 v[26:27], v[44:45], v[44:45], v[26:27]
	v_add_f32_e32 v28, v30, v31
	v_pk_fma_f32 v[26:27], v[46:47], v[46:47], v[26:27]
	v_mov_b32_e32 v29, v32
	v_add_f32_e32 v27, v28, v27
	v_add_f32_e32 v26, v26, v27
	ds_bpermute_b32 v27, v97, v26
	v_mov_b32_e32 v28, v38
	v_mov_b32_e32 v32, v39
	v_lshl_add_u64 v[48:49], v[54:55], 0, v[78:79]
	s_waitcnt lgkmcnt(0)
	v_add_f32_e32 v26, v26, v27
	ds_bpermute_b32 v27, v96, v26
	s_waitcnt lgkmcnt(0)
	v_add_f32_e32 v26, v26, v27
	ds_bpermute_b32 v27, v95, v26
	s_waitcnt lgkmcnt(0)
	v_add_f32_e32 v26, v26, v27
	ds_bpermute_b32 v27, v94, v26
	s_waitcnt lgkmcnt(0)
	v_add_f32_e32 v26, v26, v27
	ds_bpermute_b32 v27, v59, v26
	s_waitcnt lgkmcnt(0)
	v_add_f32_e32 v26, v26, v27
	ds_bpermute_b32 v27, v51, v26
	s_waitcnt lgkmcnt(0)
	v_add_f32_e32 v26, v26, v27
	v_fmamk_f32 v26, v26, 0x3a800000, v220
	v_cmp_gt_f32_e32 vcc, s93, v26
	v_mul_f32_e32 v27, 0x4b800000, v26
	s_nop 0
	v_cndmask_b32_e32 v26, v26, v27, vcc
	v_rsq_f32_e32 v26, v26
	s_nop 0
	v_mul_f32_e32 v27, 0x45800000, v26
	v_cndmask_b32_e32 v30, v26, v27, vcc
	v_mov_b32_e32 v26, v34
	v_mov_b32_e32 v27, v36
	v_pk_mul_f32 v[26:27], v[30:31], v[26:27] op_sel_hi:[0,1]
	v_pk_mul_f32 v[28:29], v[30:31], v[28:29] op_sel_hi:[0,1]
	v_mov_b32_e32 v36, v35
	v_pk_fma_f32 v[28:29], v[66:67], v[28:29], v[8:9]
	v_pk_fma_f32 v[26:27], v[68:69], v[26:27], v[6:7]
	v_pk_mul_f32 v[34:35], v[30:31], v[36:37] op_sel_hi:[0,1]
	v_pk_mul_f32 v[32:33], v[30:31], v[32:33] op_sel_hi:[0,1]
	v_pk_fma_f32 v[32:33], v[62:63], v[32:33], v[4:5]
	v_pk_fma_f32 v[34:35], v[64:65], v[34:35], v[2:3]
	v_cvt_pk_bf16_f32 v26, v26, v27
	v_cvt_pk_bf16_f32 v27, v28, v29
	v_lshlrev_b32_e32 v36, 16, v21
	v_cvt_pk_bf16_f32 v28, v34, v35
	v_cvt_pk_bf16_f32 v29, v32, v33
	global_store_dwordx4 v[48:49], v[26:29], off
	v_and_b32_e32 v35, 0xffff0000, v18
	v_and_b32_e32 v34, 0xffff0000, v20
	v_mov_b32_e32 v26, v41
	v_mov_b32_e32 v27, v43
	v_mov_b32_e32 v28, v45
	v_mov_b32_e32 v29, v47
	v_pk_mul_f32 v[26:27], v[30:31], v[26:27] op_sel_hi:[0,1]
	v_pk_mul_f32 v[28:29], v[30:31], v[28:29] op_sel_hi:[0,1]
	v_mov_b32_e32 v41, v42
	v_mov_b32_e32 v45, v46
	v_pk_fma_f32 v[28:29], v[74:75], v[28:29], v[16:17]
	v_pk_fma_f32 v[26:27], v[76:77], v[26:27], v[14:15]
	v_pk_mul_f32 v[32:33], v[30:31], v[40:41] op_sel_hi:[0,1]
	v_pk_mul_f32 v[30:31], v[30:31], v[44:45] op_sel_hi:[0,1]
	v_pk_fma_f32 v[30:31], v[70:71], v[30:31], v[12:13]
	v_pk_fma_f32 v[32:33], v[72:73], v[32:33], v[10:11]
	v_cvt_pk_bf16_f32 v26, v26, v27
	v_cvt_pk_bf16_f32 v27, v28, v29
	v_lshlrev_b32_e32 v37, 16, v19
	v_cvt_pk_bf16_f32 v28, v32, v33
	v_cvt_pk_bf16_f32 v29, v30, v31
	global_store_dwordx4 v[48:49], v[26:29], off offset:1024
	v_lshlrev_b32_e32 v30, 16, v23
	v_lshlrev_b32_e32 v31, 16, v25
	v_and_b32_e32 v29, 0xffff0000, v24
	v_and_b32_e32 v28, 0xffff0000, v22
	v_lshlrev_b32_e32 v27, 16, v24
	v_lshlrev_b32_e32 v26, 16, v22
	v_and_b32_e32 v24, 0xffff0000, v23
	v_pk_mul_f32 v[22:23], v[28:29], v[28:29]
	v_lshlrev_b32_e32 v33, 16, v18
	v_pk_fma_f32 v[22:23], v[26:27], v[26:27], v[22:23]
	v_lshlrev_b32_e32 v32, 16, v20
	v_and_b32_e32 v18, 0xffff0000, v21
	v_pk_mul_f32 v[20:21], v[34:35], v[34:35]
	v_and_b32_e32 v25, 0xffff0000, v25
	v_pk_fma_f32 v[22:23], v[30:31], v[30:31], v[22:23]
	v_pk_fma_f32 v[20:21], v[32:33], v[32:33], v[20:21]
	v_pk_fma_f32 v[22:23], v[24:25], v[24:25], v[22:23]
	v_and_b32_e32 v19, 0xffff0000, v19
	v_pk_fma_f32 v[20:21], v[36:37], v[36:37], v[20:21]
	v_add_f32_e32 v22, v22, v23
	v_pk_fma_f32 v[20:21], v[18:19], v[18:19], v[20:21]
	v_mov_b32_e32 v39, v28
	v_add_f32_e32 v21, v22, v21
	v_add_f32_e32 v20, v20, v21
	ds_bpermute_b32 v21, v97, v20
	v_mov_b32_e32 v41, v24
	v_mov_b32_e32 v28, v27
	v_mov_b32_e32 v24, v31
	v_mov_b32_e32 v38, v26
	s_waitcnt lgkmcnt(0)
	v_add_f32_e32 v20, v20, v21
	ds_bpermute_b32 v21, v96, v20
	v_mov_b32_e32 v40, v30
	v_lshl_add_u64 v[22:23], v[54:55], 0, v[60:61]
	s_waitcnt lgkmcnt(0)
	v_add_f32_e32 v20, v20, v21
	ds_bpermute_b32 v21, v95, v20
	s_waitcnt lgkmcnt(0)
	v_add_f32_e32 v20, v20, v21
	ds_bpermute_b32 v21, v94, v20
	s_waitcnt lgkmcnt(0)
	v_add_f32_e32 v20, v20, v21
	ds_bpermute_b32 v21, v59, v20
	s_waitcnt lgkmcnt(0)
	v_add_f32_e32 v20, v20, v21
	ds_bpermute_b32 v21, v51, v20
	s_waitcnt lgkmcnt(0)
	v_add_f32_e32 v20, v20, v21
	v_fmamk_f32 v20, v20, 0x3a800000, v220
	v_cmp_gt_f32_e32 vcc, s93, v20
	v_mul_f32_e32 v21, 0x4b800000, v20
	s_nop 0
	v_cndmask_b32_e32 v20, v20, v21, vcc
	v_rsq_f32_e32 v20, v20
	s_nop 0
	v_mul_f32_e32 v21, 0x45800000, v20
	v_cndmask_b32_e32 v20, v20, v21, vcc
	v_pk_mul_f32 v[26:27], v[20:21], v[28:29] op_sel_hi:[0,1]
	v_pk_mul_f32 v[24:25], v[20:21], v[24:25] op_sel_hi:[0,1]
	v_pk_mul_f32 v[38:39], v[20:21], v[38:39] op_sel_hi:[0,1]
	v_pk_mul_f32 v[40:41], v[20:21], v[40:41] op_sel_hi:[0,1]
	v_pk_fma_f32 v[24:25], v[62:63], v[24:25], v[4:5]
	v_pk_fma_f32 v[4:5], v[64:65], v[26:27], v[2:3]
	v_pk_fma_f32 v[8:9], v[66:67], v[40:41], v[8:9]
	v_pk_fma_f32 v[6:7], v[68:69], v[38:39], v[6:7]
	s_nop 0
	v_cvt_pk_bf16_f32 v2, v6, v7
	v_cvt_pk_bf16_f32 v3, v8, v9
	v_cvt_pk_bf16_f32 v4, v4, v5
	v_cvt_pk_bf16_f32 v5, v24, v25
	global_store_dwordx4 v[22:23], v[2:5], off
	s_nop 1
	v_mov_b32_e32 v2, v33
	v_mov_b32_e32 v3, v35
	v_mov_b32_e32 v4, v37
	v_mov_b32_e32 v5, v19
	v_pk_mul_f32 v[2:3], v[20:21], v[2:3] op_sel_hi:[0,1]
	v_pk_mul_f32 v[4:5], v[20:21], v[4:5] op_sel_hi:[0,1]
	v_mov_b32_e32 v33, v34
	v_mov_b32_e32 v37, v18
	v_pk_fma_f32 v[4:5], v[74:75], v[4:5], v[16:17]
	v_pk_fma_f32 v[2:3], v[76:77], v[2:3], v[14:15]
	v_pk_mul_f32 v[6:7], v[20:21], v[32:33] op_sel_hi:[0,1]
	v_pk_mul_f32 v[8:9], v[20:21], v[36:37] op_sel_hi:[0,1]
	v_pk_fma_f32 v[8:9], v[70:71], v[8:9], v[12:13]
	v_pk_fma_f32 v[6:7], v[72:73], v[6:7], v[10:11]
	v_cvt_pk_bf16_f32 v2, v2, v3
	v_cvt_pk_bf16_f32 v3, v4, v5
	s_nop 0
	v_cvt_pk_bf16_f32 v4, v6, v7
	v_cvt_pk_bf16_f32 v5, v8, v9
	global_store_dwordx4 v[22:23], v[2:5], off offset:1024
	s_branch .LBB0_1141
